# SGU spatial-mixing epilogue rewritten: operands loaded in two batches with counted waits instead of 128 load-wait-store chains
# speedup vs baseline: 1.0385x; 1.0139x over previous
; #define LAS __attribute__((address_space(3)))
; __device__ __forceinline__ void mix_phase(const int TID, const int BID, PP p, LAS unsigned char* lds) {
;     ...
;               *(LAS u32x4*)(Wsl + i * 272 + j0 * 2) = w;
;           } }
;         { const int j = t & 127, cgp = t >> 7; const bf16_t* vsrc = uv + (size_t)(n * 128 + j) * 4096 + 2048 + g * 256;
; #pragma unroll
;           for (int q = 0; q < 8; ++q) {
;               const int c = (q * 4 + cgp) * 8; const u32x4 v = *(const u32x4*)(vsrc + c);
; #pragma unroll
;               for (int e = 0; e < 4; ++e) { *(LAS bf16_t*)(Vt + (c + 2 * e) * 272 + j * 2) = (bf16_t)(v[e] & 0xffffu); *(LAS bf16_t*)(Vt + (c + 2 * e + 1) * 272 + j * 2) = (bf16_t)(v[e] >> 16); }
;           } }
;         __syncthreads();
;         f32x16 acc[4];
; #pragma unroll
;         for (int ct = 0; ct < 4; ++ct)
; #pragma unroll
;             for (int i = 0; i < 16; ++i) acc[ct][i] = 0.f;
; #pragma unroll
;         for (int ks = 0; ks < 8; ++ks) {
;             const bf16x8 Af = *(const LAS bf16x8*)(Wsl + (it_ * 32 + rr) * 272 + (ks * 16 + g2 * 8) * 2);
; #pragma unroll
;             for (int ct = 0; ct < 4; ++ct) { const bf16x8 Bf = *(const LAS bf16x8*)(Vt + (ch * 128 + ct * 32 + rr) * 272 + (ks * 16 + g2 * 8) * 2); acc[ct] = __builtin_amdgcn_mfma_f32_32x32x16_bf16(Af, Bf, acc[ct], 0, 0, 0); }
.LBB0_834:
	s_or_b64 exec, exec, s[10:11]
	ds_write_b128 v89, v[0:3] offset:1024
	v_lshl_or_b32 v0, s18, 7, v75
	v_ashrrev_i32_e32 v1, 31, v0
	v_lshlrev_b64 v[0:1], 13, v[0:1]
	v_lshl_add_u64 v[0:1], s[14:15], 0, v[0:1]
	s_lshl_b32 s10, s0, 9
	s_mov_b32 s11, s73
	v_lshl_add_u64 v[0:1], v[0:1], 0, s[10:11]
	v_lshl_add_u64 v[2:3], v[68:69], 1, v[0:1]
	s_mov_b64 s[10:11], 0x1000
	s_movk_i32 s1, 0x1000
	v_lshl_add_u64 v[0:1], v[2:3], 0, s[10:11]
	v_add_co_u32_e64 v2, s[10:11], s1, v2
	v_add_u32_e32 v6, v85, v77
	s_nop 0
	v_addc_co_u32_e64 v3, s[10:11], 0, v3, s[10:11]
	global_load_dwordx4 v[2:5], v[2:3], off
	v_readlane_b32 s10, v254, 32
	v_readlane_b32 s11, v254, 33
	s_ashr_i32 s19, s18, 31
	s_lshl_b64 s[18:19], s[18:19], 7
	v_mov_b32_e32 v117, s19
	v_or_b32_e32 v116, s18, v72
	s_add_i32 s22, s22, s70
	s_cmpk_gt_i32 s22, 0x1ff
	s_waitcnt vmcnt(0)
	ds_write_b16 v6, v2 offset:35840
	ds_write_b16_d16_hi v6, v2 offset:36112
	ds_write_b16 v6, v3 offset:36384
	ds_write_b16_d16_hi v6, v3 offset:36656
	ds_write_b16 v6, v4 offset:36928
	ds_write_b16_d16_hi v6, v4 offset:37200
	ds_write_b16 v6, v5 offset:37472
	ds_write_b16_d16_hi v6, v5 offset:37744
	global_load_dwordx4 v[2:5], v[0:1], off offset:64
	s_waitcnt vmcnt(0)
	ds_write_b16 v91, v2 offset:35840
	ds_write_b16_d16_hi v91, v2 offset:36112
	ds_write_b16 v6, v3 offset:45088
	ds_write_b16_d16_hi v6, v3 offset:45360
	ds_write_b16 v6, v4 offset:45632
	ds_write_b16_d16_hi v6, v4 offset:45904
	ds_write_b16 v6, v5 offset:46176
	ds_write_b16_d16_hi v6, v5 offset:46448
	global_load_dwordx4 v[2:5], v[0:1], off offset:128
	s_waitcnt vmcnt(0)
	ds_write_b16 v93, v2 offset:35840
	ds_write_b16_d16_hi v93, v2 offset:36112
	ds_write_b16 v6, v3 offset:53792
	ds_write_b16_d16_hi v6, v3 offset:54064
	ds_write_b16 v6, v4 offset:54336
	ds_write_b16_d16_hi v6, v4 offset:54608
	ds_write_b16 v6, v5 offset:54880
	ds_write_b16_d16_hi v6, v5 offset:55152
	global_load_dwordx4 v[2:5], v[0:1], off offset:192
	s_waitcnt vmcnt(0)
	ds_write_b16 v95, v2 offset:35840
	ds_write_b16_d16_hi v95, v2 offset:36112
	ds_write_b16 v6, v3 offset:62496
	ds_write_b16_d16_hi v6, v3 offset:62768
	ds_write_b16 v6, v4 offset:63040
	ds_write_b16_d16_hi v6, v4 offset:63312
	ds_write_b16 v6, v5 offset:63584
	ds_write_b16_d16_hi v6, v5 offset:63856
	global_load_dwordx4 v[2:5], v[0:1], off offset:256
	s_waitcnt vmcnt(0)
	ds_write_b16 v97, v2 offset:35840
	ds_write_b16_d16_hi v97, v2 offset:36112
	ds_write_b16 v99, v3 offset:35360
	ds_write_b16_d16_hi v99, v3 offset:35632
	ds_write_b16 v99, v4 offset:35904
	ds_write_b16_d16_hi v99, v4 offset:36176
	ds_write_b16 v99, v5 offset:36448
	ds_write_b16_d16_hi v99, v5 offset:36720
	global_load_dwordx4 v[2:5], v[0:1], off offset:320
	s_waitcnt vmcnt(0)
	ds_write_b16 v101, v2 offset:35840
	ds_write_b16_d16_hi v101, v2 offset:36112
	ds_write_b16 v99, v3 offset:44064
	ds_write_b16_d16_hi v99, v3 offset:44336
	ds_write_b16 v99, v4 offset:44608
	ds_write_b16_d16_hi v99, v4 offset:44880
	ds_write_b16 v99, v5 offset:45152
	ds_write_b16_d16_hi v99, v5 offset:45424
	global_load_dwordx4 v[2:5], v[0:1], off offset:384
	s_waitcnt vmcnt(0)
	ds_write_b16 v160, v2 offset:35840
	ds_write_b16_d16_hi v160, v2 offset:36112
	ds_write_b16 v99, v3 offset:52768
	ds_write_b16_d16_hi v99, v3 offset:53040
	ds_write_b16 v99, v4 offset:53312
	ds_write_b16_d16_hi v99, v4 offset:53584
	ds_write_b16 v99, v5 offset:53856
	ds_write_b16_d16_hi v99, v5 offset:54128
	global_load_dwordx4 v[0:3], v[0:1], off offset:448
	s_waitcnt vmcnt(0)
	ds_write_b16 v182, v0 offset:35840
	ds_write_b16_d16_hi v182, v0 offset:36112
	ds_write_b16 v99, v1 offset:61472
	ds_write_b16_d16_hi v99, v1 offset:61744
	ds_write_b16 v99, v2 offset:62016
	ds_write_b16_d16_hi v99, v2 offset:62288
	ds_write_b16 v99, v3 offset:62560
	ds_write_b16_d16_hi v99, v3 offset:62832
	s_waitcnt lgkmcnt(0)
	s_barrier
	ds_read_b128 v[0:3], v183 offset:1024
	ds_read_b128 v[102:105], v183 offset:1056
	ds_read_b128 v[4:7], v184 offset:35840
	ds_read_b128 v[106:109], v184 offset:35872
	s_waitcnt lgkmcnt(1)
	v_mfma_f32_32x32x16_bf16 v[48:63], v[0:3], v[4:7], 0
	ds_read_b128 v[4:7], v184 offset:44544
	s_waitcnt lgkmcnt(1)
	v_mfma_f32_32x32x16_bf16 v[48:63], v[102:105], v[106:109], v[48:63]
	ds_read_b128 v[106:109], v184 offset:44576
	s_waitcnt lgkmcnt(1)
	v_mfma_f32_32x32x16_bf16 v[32:47], v[0:3], v[4:7], 0
	ds_read_b128 v[4:7], v184 offset:53248
	s_waitcnt lgkmcnt(1)
	v_mfma_f32_32x32x16_bf16 v[32:47], v[102:105], v[106:109], v[32:47]
	ds_read_b128 v[106:109], v184 offset:53280
	s_waitcnt lgkmcnt(1)
	v_mfma_f32_32x32x16_bf16 v[16:31], v[0:3], v[4:7], 0
	ds_read_b128 v[4:7], v184 offset:61952
	s_waitcnt lgkmcnt(1)
	v_mfma_f32_32x32x16_bf16 v[16:31], v[102:105], v[106:109], v[16:31]
	ds_read_b128 v[106:109], v184 offset:61984
	s_waitcnt lgkmcnt(1)
	v_mfma_f32_32x32x16_bf16 v[0:15], v[0:3], v[4:7], 0
	s_waitcnt lgkmcnt(0)
	v_mfma_f32_32x32x16_bf16 v[0:15], v[102:105], v[106:109], v[0:15]
	ds_read_b128 v[102:105], v183 offset:1088
	ds_read_b128 v[106:109], v184 offset:35904
	s_waitcnt lgkmcnt(0)
	v_mfma_f32_32x32x16_bf16 v[48:63], v[102:105], v[106:109], v[48:63]
	ds_read_b128 v[106:109], v184 offset:44608
	s_waitcnt lgkmcnt(0)
	v_mfma_f32_32x32x16_bf16 v[32:47], v[102:105], v[106:109], v[32:47]
	ds_read_b128 v[106:109], v184 offset:53312
	s_waitcnt lgkmcnt(0)
	v_mfma_f32_32x32x16_bf16 v[16:31], v[102:105], v[106:109], v[16:31]
	ds_read_b128 v[106:109], v184 offset:62016
	s_waitcnt lgkmcnt(0)
	v_mfma_f32_32x32x16_bf16 v[0:15], v[102:105], v[106:109], v[0:15]
	ds_read_b128 v[102:105], v183 offset:1120
	ds_read_b128 v[106:109], v184 offset:35936
	s_waitcnt lgkmcnt(0)
; #define LAS __attribute__((address_space(3)))
; __device__ __forceinline__ unsigned cvt_pk_bf16(float lo, float hi) { unsigned r; asm volatile("v_cvt_pk_bf16_f32 %0, %1, %2" : "=v"(r) : "v"(lo), "v"(hi)); return r; }
; __device__ __forceinline__ void mix_phase(const int TID, const int BID, PP p, LAS unsigned char* lds) {
;     ...
;         for (int ks = 0; ks < 8; ++ks) {
;             const bf16x8 Af = *(const LAS bf16x8*)(Wsl + (it_ * 32 + rr) * 272 + (ks * 16 + g2 * 8) * 2);
; #pragma unroll
;             for (int ct = 0; ct < 4; ++ct) { const bf16x8 Bf = *(const LAS bf16x8*)(Vt + (ch * 128 + ct * 32 + rr) * 272 + (ks * 16 + g2 * 8) * 2); acc[ct] = __builtin_amdgcn_mfma_f32_32x32x16_bf16(Af, Bf, acc[ct], 0, 0, 0); }
;         }
; #pragma unroll
;         for (int ct = 0; ct < 4; ++ct) {
;             const int cg_ = g * 256 + ch * 128 + ct * 32 + rr; const float gain = p->sgu_v_gain[cg_];
; #pragma unroll
;             for (int r = 0; r < 16; ++r) {
;                 const int i = it_ * 32 + (r & 3) + 8 * (r >> 2) + 4 * g2; const size_t tok = (size_t)n * 128 + i;
;                 const float mixed = gain * acc[ct][r] + p->sgu_b_s[g * 128 + i];
;                 const float uval = __uint_as_float((unsigned)uv[tok * 4096 + cg_] << 16);
;                 AB[tok * 2048 + cg_] = (bf16_t)(cvt_pk_bf16(uval * mixed, 0.f) & 0xffffu);
	v_mfma_f32_32x32x16_bf16 v[48:63], v[102:105], v[106:109], v[48:63]
	ds_read_b128 v[106:109], v184 offset:44640
	s_waitcnt lgkmcnt(0)
	v_mfma_f32_32x32x16_bf16 v[32:47], v[102:105], v[106:109], v[32:47]
	ds_read_b128 v[106:109], v184 offset:53344
	s_waitcnt lgkmcnt(0)
	v_mfma_f32_32x32x16_bf16 v[16:31], v[102:105], v[106:109], v[16:31]
	ds_read_b128 v[106:109], v184 offset:62048
	s_waitcnt lgkmcnt(0)
	v_mfma_f32_32x32x16_bf16 v[0:15], v[102:105], v[106:109], v[0:15]
	ds_read_b128 v[102:105], v183 offset:1152
	ds_read_b128 v[106:109], v184 offset:35968
	s_waitcnt lgkmcnt(0)
	v_mfma_f32_32x32x16_bf16 v[48:63], v[102:105], v[106:109], v[48:63]
	ds_read_b128 v[106:109], v184 offset:44672
	s_waitcnt lgkmcnt(0)
	v_mfma_f32_32x32x16_bf16 v[32:47], v[102:105], v[106:109], v[32:47]
	ds_read_b128 v[106:109], v184 offset:53376
	s_waitcnt lgkmcnt(0)
	v_mfma_f32_32x32x16_bf16 v[16:31], v[102:105], v[106:109], v[16:31]
	ds_read_b128 v[106:109], v184 offset:62080
	s_waitcnt lgkmcnt(0)
	v_mfma_f32_32x32x16_bf16 v[0:15], v[102:105], v[106:109], v[0:15]
	ds_read_b128 v[102:105], v183 offset:1184
	ds_read_b128 v[106:109], v184 offset:36000
	s_waitcnt lgkmcnt(0)
	v_mfma_f32_32x32x16_bf16 v[48:63], v[102:105], v[106:109], v[48:63]
	ds_read_b128 v[106:109], v184 offset:44704
	s_waitcnt lgkmcnt(0)
	v_mfma_f32_32x32x16_bf16 v[32:47], v[102:105], v[106:109], v[32:47]
	ds_read_b128 v[106:109], v184 offset:53408
	s_waitcnt lgkmcnt(0)
	v_mfma_f32_32x32x16_bf16 v[16:31], v[102:105], v[106:109], v[16:31]
	ds_read_b128 v[106:109], v184 offset:62112
	s_waitcnt lgkmcnt(0)
	v_mfma_f32_32x32x16_bf16 v[0:15], v[102:105], v[106:109], v[0:15]
	ds_read_b128 v[102:105], v183 offset:1216
	ds_read_b128 v[106:109], v184 offset:36032
	s_waitcnt lgkmcnt(0)
	v_mfma_f32_32x32x16_bf16 v[48:63], v[102:105], v[106:109], v[48:63]
	ds_read_b128 v[106:109], v184 offset:44736
	s_waitcnt lgkmcnt(0)
	v_mfma_f32_32x32x16_bf16 v[32:47], v[102:105], v[106:109], v[32:47]
	ds_read_b128 v[106:109], v184 offset:53440
	s_waitcnt lgkmcnt(0)
	v_mfma_f32_32x32x16_bf16 v[16:31], v[102:105], v[106:109], v[16:31]
	ds_read_b128 v[106:109], v184 offset:62144
	s_waitcnt lgkmcnt(0)
	v_mfma_f32_32x32x16_bf16 v[0:15], v[102:105], v[106:109], v[0:15]
	ds_read_b128 v[102:105], v183 offset:1248
	ds_read_b128 v[106:109], v184 offset:36064
	s_waitcnt lgkmcnt(0)
	v_mfma_f32_32x32x16_bf16 v[48:63], v[102:105], v[106:109], v[48:63]
	ds_read_b128 v[106:109], v184 offset:44768
	s_waitcnt lgkmcnt(0)
	v_mfma_f32_32x32x16_bf16 v[32:47], v[102:105], v[106:109], v[32:47]
	ds_read_b128 v[106:109], v184 offset:53472
	s_waitcnt lgkmcnt(0)
	v_mfma_f32_32x32x16_bf16 v[16:31], v[102:105], v[106:109], v[16:31]
	ds_read_b128 v[106:109], v184 offset:62176
	s_waitcnt lgkmcnt(0)
	v_mfma_f32_32x32x16_bf16 v[0:15], v[102:105], v[106:109], v[0:15]
	v_lshl_add_u32 v102, s0, 8, v79
	s_load_dwordx2 s[0:1], s[10:11], 0x58
	s_nop 0
	s_load_dwordx2 s[10:11], s[10:11], 0x68
	v_readlane_b32 s20, v254, 38
	v_readlane_b32 s21, v254, 39
	v_lshlrev_b32_e32 v103, 2, v102
	v_or_b32_e32 v104, s72, v70
	v_lshlrev_b32_e32 v104, 2, v104
	v_or_b32_e32 v105, s18, v70
	v_lshlrev_b32_e32 v106, 13, v105
	v_lshl_add_u32 v106, v102, 1, v106
	v_lshlrev_b32_e32 v107, 12, v105
	v_lshl_add_u32 v107, v102, 1, v107
	v_mov_b32_e32 v118, v106
	v_add_u32_e32 v119, 0x2000, v106
	v_add_u32_e32 v120, 0x4000, v106
	v_add_u32_e32 v121, 0x6000, v106
	v_add_u32_e32 v122, 0x10000, v106
	v_add_u32_e32 v123, 0x12000, v106
	v_add_u32_e32 v124, 0x14000, v106
	v_add_u32_e32 v125, 0x16000, v106
	v_add_u32_e32 v126, 0x20000, v106
	v_add_u32_e32 v127, 0x22000, v106
	v_add_u32_e32 v128, 0x24000, v106
	v_add_u32_e32 v129, 0x26000, v106
	v_add_u32_e32 v130, 0x30000, v106
	v_add_u32_e32 v131, 0x32000, v106
	v_add_u32_e32 v132, 0x34000, v106
	v_add_u32_e32 v133, 0x36000, v106
	global_load_ushort v208, v118, s[14:15]
	global_load_ushort v209, v119, s[14:15]
	global_load_ushort v210, v120, s[14:15]
	global_load_ushort v211, v121, s[14:15]
	global_load_ushort v212, v122, s[14:15]
	global_load_ushort v213, v123, s[14:15]
	global_load_ushort v214, v124, s[14:15]
	global_load_ushort v215, v125, s[14:15]
	global_load_ushort v216, v126, s[14:15]
	global_load_ushort v217, v127, s[14:15]
	global_load_ushort v218, v128, s[14:15]
	global_load_ushort v219, v129, s[14:15]
	global_load_ushort v220, v130, s[14:15]
	global_load_ushort v221, v131, s[14:15]
	global_load_ushort v222, v132, s[14:15]
	global_load_ushort v223, v133, s[14:15]
	global_load_ushort v224, v118, s[14:15] offset:64
	global_load_ushort v225, v119, s[14:15] offset:64
	global_load_ushort v226, v120, s[14:15] offset:64
	global_load_ushort v227, v121, s[14:15] offset:64
	global_load_ushort v228, v122, s[14:15] offset:64
	global_load_ushort v229, v123, s[14:15] offset:64
	global_load_ushort v230, v124, s[14:15] offset:64
	global_load_ushort v231, v125, s[14:15] offset:64
	global_load_ushort v232, v126, s[14:15] offset:64
	global_load_ushort v233, v127, s[14:15] offset:64
	global_load_ushort v234, v128, s[14:15] offset:64
	global_load_ushort v235, v129, s[14:15] offset:64
	global_load_ushort v236, v130, s[14:15] offset:64
	global_load_ushort v237, v131, s[14:15] offset:64
	global_load_ushort v238, v132, s[14:15] offset:64
	global_load_ushort v239, v133, s[14:15] offset:64
	s_waitcnt lgkmcnt(0)
; __device__ __forceinline__ unsigned cvt_pk_bf16(float lo, float hi) { unsigned r; asm volatile("v_cvt_pk_bf16_f32 %0, %1, %2" : "=v"(r) : "v"(lo), "v"(hi)); return r; }
; __device__ __forceinline__ void mix_phase(const int TID, const int BID, PP p, LAS unsigned char* lds) {
;     ...
;         for (int ct = 0; ct < 4; ++ct) {
;             const int cg_ = g * 256 + ch * 128 + ct * 32 + rr; const float gain = p->sgu_v_gain[cg_];
; #pragma unroll
;             for (int r = 0; r < 16; ++r) {
;                 const int i = it_ * 32 + (r & 3) + 8 * (r >> 2) + 4 * g2; const size_t tok = (size_t)n * 128 + i;
;                 const float mixed = gain * acc[ct][r] + p->sgu_b_s[g * 128 + i];
;                 const float uval = __uint_as_float((unsigned)uv[tok * 4096 + cg_] << 16);
;                 AB[tok * 2048 + cg_] = (bf16_t)(cvt_pk_bf16(uval * mixed, 0.f) & 0xffffu);
	global_load_dword v110, v103, s[0:1]
	global_load_dword v111, v103, s[0:1] offset:128
	global_load_dword v112, v103, s[0:1] offset:256
	global_load_dword v113, v103, s[0:1] offset:384
	global_load_dword v166, v104, s[10:11]
	global_load_dword v167, v104, s[10:11] offset:4
	global_load_dword v168, v104, s[10:11] offset:8
	global_load_dword v169, v104, s[10:11] offset:12
	global_load_dword v170, v104, s[10:11] offset:32
	global_load_dword v171, v104, s[10:11] offset:36
	global_load_dword v172, v104, s[10:11] offset:40
	global_load_dword v173, v104, s[10:11] offset:44
	global_load_dword v174, v104, s[10:11] offset:64
	global_load_dword v175, v104, s[10:11] offset:68
	global_load_dword v176, v104, s[10:11] offset:72
	global_load_dword v177, v104, s[10:11] offset:76
	global_load_dword v178, v104, s[10:11] offset:96
	global_load_dword v179, v104, s[10:11] offset:100
	global_load_dword v180, v104, s[10:11] offset:104
	global_load_dword v181, v104, s[10:11] offset:108
	v_mov_b32_e32 v134, v107
	v_add_u32_e32 v135, 0x1000, v107
	v_add_u32_e32 v136, 0x2000, v107
	v_add_u32_e32 v137, 0x3000, v107
	v_add_u32_e32 v138, 0x8000, v107
	v_add_u32_e32 v139, 0x9000, v107
	v_add_u32_e32 v140, 0xa000, v107
	v_add_u32_e32 v141, 0xb000, v107
	v_add_u32_e32 v142, 0x10000, v107
	v_add_u32_e32 v143, 0x11000, v107
	v_add_u32_e32 v144, 0x12000, v107
	v_add_u32_e32 v145, 0x13000, v107
	v_add_u32_e32 v146, 0x18000, v107
	v_add_u32_e32 v147, 0x19000, v107
	v_add_u32_e32 v148, 0x1a000, v107
	v_add_u32_e32 v149, 0x1b000, v107
	s_waitcnt vmcnt(0)
	global_load_ushort v240, v118, s[14:15] offset:128
	global_load_ushort v241, v119, s[14:15] offset:128
	global_load_ushort v242, v120, s[14:15] offset:128
	global_load_ushort v243, v121, s[14:15] offset:128
	global_load_ushort v244, v122, s[14:15] offset:128
	global_load_ushort v245, v123, s[14:15] offset:128
	global_load_ushort v246, v124, s[14:15] offset:128
	global_load_ushort v247, v125, s[14:15] offset:128
	global_load_ushort v248, v126, s[14:15] offset:128
	global_load_ushort v249, v127, s[14:15] offset:128
	global_load_ushort v250, v128, s[14:15] offset:128
	global_load_ushort v251, v129, s[14:15] offset:128
	global_load_ushort v252, v130, s[14:15] offset:128
	global_load_ushort v253, v131, s[14:15] offset:128
	global_load_ushort v198, v132, s[14:15] offset:128
	global_load_ushort v199, v133, s[14:15] offset:128
	global_load_ushort v150, v118, s[14:15] offset:192
	global_load_ushort v151, v119, s[14:15] offset:192
	global_load_ushort v152, v120, s[14:15] offset:192
	global_load_ushort v153, v121, s[14:15] offset:192
	global_load_ushort v154, v122, s[14:15] offset:192
	global_load_ushort v155, v123, s[14:15] offset:192
	global_load_ushort v156, v124, s[14:15] offset:192
	global_load_ushort v157, v125, s[14:15] offset:192
	global_load_ushort v158, v126, s[14:15] offset:192
	global_load_ushort v159, v127, s[14:15] offset:192
	global_load_ushort v114, v128, s[14:15] offset:192
	global_load_ushort v115, v129, s[14:15] offset:192
	global_load_ushort v196, v130, s[14:15] offset:192
	global_load_ushort v197, v131, s[14:15] offset:192
	global_load_ushort v200, v132, s[14:15] offset:192
	global_load_ushort v201, v133, s[14:15] offset:192
	v_fma_f32 v48, v48, v110, v166
	v_fma_f32 v49, v49, v110, v167
	v_fma_f32 v50, v50, v110, v168
	v_fma_f32 v51, v51, v110, v169
	v_fma_f32 v52, v52, v110, v170
	v_fma_f32 v53, v53, v110, v171
	v_fma_f32 v54, v54, v110, v172
	v_fma_f32 v55, v55, v110, v173
	v_fma_f32 v56, v56, v110, v174
	v_fma_f32 v57, v57, v110, v175
	v_fma_f32 v58, v58, v110, v176
	v_fma_f32 v59, v59, v110, v177
	v_fma_f32 v60, v60, v110, v178
	v_fma_f32 v61, v61, v110, v179
	v_fma_f32 v62, v62, v110, v180
	v_fma_f32 v63, v63, v110, v181
	v_fma_f32 v32, v32, v111, v166
	v_fma_f32 v33, v33, v111, v167
	v_fma_f32 v34, v34, v111, v168
	v_fma_f32 v35, v35, v111, v169
	v_fma_f32 v36, v36, v111, v170
	v_fma_f32 v37, v37, v111, v171
	v_fma_f32 v38, v38, v111, v172
	v_fma_f32 v39, v39, v111, v173
	v_fma_f32 v40, v40, v111, v174
	v_fma_f32 v41, v41, v111, v175
	v_fma_f32 v42, v42, v111, v176
	v_fma_f32 v43, v43, v111, v177
	v_fma_f32 v44, v44, v111, v178
	v_fma_f32 v45, v45, v111, v179
	v_fma_f32 v46, v46, v111, v180
	v_fma_f32 v47, v47, v111, v181
	v_fma_f32 v16, v16, v112, v166
	v_fma_f32 v17, v17, v112, v167
	v_fma_f32 v18, v18, v112, v168
	v_fma_f32 v19, v19, v112, v169
	v_fma_f32 v20, v20, v112, v170
	v_fma_f32 v21, v21, v112, v171
	v_fma_f32 v22, v22, v112, v172
	v_fma_f32 v23, v23, v112, v173
	v_fma_f32 v24, v24, v112, v174
	v_fma_f32 v25, v25, v112, v175
	v_fma_f32 v26, v26, v112, v176
	v_fma_f32 v27, v27, v112, v177
	v_fma_f32 v28, v28, v112, v178
	v_fma_f32 v29, v29, v112, v179
	v_fma_f32 v30, v30, v112, v180
	v_fma_f32 v31, v31, v112, v181
	v_fma_f32 v0, v0, v113, v166
	v_fma_f32 v1, v1, v113, v167
	v_fma_f32 v2, v2, v113, v168
	v_fma_f32 v3, v3, v113, v169
	v_fma_f32 v4, v4, v113, v170
	v_fma_f32 v5, v5, v113, v171
	v_fma_f32 v6, v6, v113, v172
	v_fma_f32 v7, v7, v113, v173
	v_fma_f32 v8, v8, v113, v174
	v_fma_f32 v9, v9, v113, v175
	v_fma_f32 v10, v10, v113, v176
	v_fma_f32 v11, v11, v113, v177
	v_fma_f32 v12, v12, v113, v178
	v_fma_f32 v13, v13, v113, v179
	v_fma_f32 v14, v14, v113, v180
	v_fma_f32 v15, v15, v113, v181
	v_lshlrev_b32_e32 v208, 16, v208
	v_mul_f32_e32 v208, v48, v208
	v_cvt_pk_bf16_f32 v208, v208, v161
	v_lshlrev_b32_e32 v209, 16, v209
	v_mul_f32_e32 v209, v49, v209
	v_cvt_pk_bf16_f32 v209, v209, v161
	v_lshlrev_b32_e32 v210, 16, v210
	v_mul_f32_e32 v210, v50, v210
	v_cvt_pk_bf16_f32 v210, v210, v161
	v_lshlrev_b32_e32 v211, 16, v211
	v_mul_f32_e32 v211, v51, v211
	v_cvt_pk_bf16_f32 v211, v211, v161
; __device__ __forceinline__ unsigned cvt_pk_bf16(float lo, float hi) { unsigned r; asm volatile("v_cvt_pk_bf16_f32 %0, %1, %2" : "=v"(r) : "v"(lo), "v"(hi)); return r; }
; __device__ __forceinline__ void mix_phase(const int TID, const int BID, PP p, LAS unsigned char* lds) {
;     ...
;         for (int ct = 0; ct < 4; ++ct) {
;             const int cg_ = g * 256 + ch * 128 + ct * 32 + rr; const float gain = p->sgu_v_gain[cg_];
; #pragma unroll
;             for (int r = 0; r < 16; ++r) {
;                 const int i = it_ * 32 + (r & 3) + 8 * (r >> 2) + 4 * g2; const size_t tok = (size_t)n * 128 + i;
;                 const float mixed = gain * acc[ct][r] + p->sgu_b_s[g * 128 + i];
;                 const float uval = __uint_as_float((unsigned)uv[tok * 4096 + cg_] << 16);
;                 AB[tok * 2048 + cg_] = (bf16_t)(cvt_pk_bf16(uval * mixed, 0.f) & 0xffffu);
;             }
	v_lshlrev_b32_e32 v212, 16, v212
	v_mul_f32_e32 v212, v52, v212
	v_cvt_pk_bf16_f32 v212, v212, v161
	v_lshlrev_b32_e32 v213, 16, v213
	v_mul_f32_e32 v213, v53, v213
	v_cvt_pk_bf16_f32 v213, v213, v161
	v_lshlrev_b32_e32 v214, 16, v214
	v_mul_f32_e32 v214, v54, v214
	v_cvt_pk_bf16_f32 v214, v214, v161
	v_lshlrev_b32_e32 v215, 16, v215
	v_mul_f32_e32 v215, v55, v215
	v_cvt_pk_bf16_f32 v215, v215, v161
	v_lshlrev_b32_e32 v216, 16, v216
	v_mul_f32_e32 v216, v56, v216
	v_cvt_pk_bf16_f32 v216, v216, v161
	v_lshlrev_b32_e32 v217, 16, v217
	v_mul_f32_e32 v217, v57, v217
	v_cvt_pk_bf16_f32 v217, v217, v161
	v_lshlrev_b32_e32 v218, 16, v218
	v_mul_f32_e32 v218, v58, v218
	v_cvt_pk_bf16_f32 v218, v218, v161
	v_lshlrev_b32_e32 v219, 16, v219
	v_mul_f32_e32 v219, v59, v219
	v_cvt_pk_bf16_f32 v219, v219, v161
	v_lshlrev_b32_e32 v220, 16, v220
	v_mul_f32_e32 v220, v60, v220
	v_cvt_pk_bf16_f32 v220, v220, v161
	v_lshlrev_b32_e32 v221, 16, v221
	v_mul_f32_e32 v221, v61, v221
	v_cvt_pk_bf16_f32 v221, v221, v161
	v_lshlrev_b32_e32 v222, 16, v222
	v_mul_f32_e32 v222, v62, v222
	v_cvt_pk_bf16_f32 v222, v222, v161
	v_lshlrev_b32_e32 v223, 16, v223
	v_mul_f32_e32 v223, v63, v223
	v_cvt_pk_bf16_f32 v223, v223, v161
	global_store_short v134, v208, s[20:21]
	global_store_short v135, v209, s[20:21]
	global_store_short v136, v210, s[20:21]
	global_store_short v137, v211, s[20:21]
	global_store_short v138, v212, s[20:21]
	global_store_short v139, v213, s[20:21]
	global_store_short v140, v214, s[20:21]
	global_store_short v141, v215, s[20:21]
	global_store_short v142, v216, s[20:21]
	global_store_short v143, v217, s[20:21]
	global_store_short v144, v218, s[20:21]
	global_store_short v145, v219, s[20:21]
	global_store_short v146, v220, s[20:21]
	global_store_short v147, v221, s[20:21]
	global_store_short v148, v222, s[20:21]
	global_store_short v149, v223, s[20:21]
	s_waitcnt vmcnt(40)
	v_lshlrev_b32_e32 v224, 16, v224
	v_mul_f32_e32 v224, v32, v224
	v_cvt_pk_bf16_f32 v224, v224, v161
	v_lshlrev_b32_e32 v225, 16, v225
	v_mul_f32_e32 v225, v33, v225
	v_cvt_pk_bf16_f32 v225, v225, v161
	v_lshlrev_b32_e32 v226, 16, v226
	v_mul_f32_e32 v226, v34, v226
	v_cvt_pk_bf16_f32 v226, v226, v161
	v_lshlrev_b32_e32 v227, 16, v227
	v_mul_f32_e32 v227, v35, v227
	v_cvt_pk_bf16_f32 v227, v227, v161
	v_lshlrev_b32_e32 v228, 16, v228
	v_mul_f32_e32 v228, v36, v228
	v_cvt_pk_bf16_f32 v228, v228, v161
	v_lshlrev_b32_e32 v229, 16, v229
	v_mul_f32_e32 v229, v37, v229
	v_cvt_pk_bf16_f32 v229, v229, v161
	v_lshlrev_b32_e32 v230, 16, v230
	v_mul_f32_e32 v230, v38, v230
	v_cvt_pk_bf16_f32 v230, v230, v161
	v_lshlrev_b32_e32 v231, 16, v231
	v_mul_f32_e32 v231, v39, v231
	v_cvt_pk_bf16_f32 v231, v231, v161
	v_lshlrev_b32_e32 v232, 16, v232
	v_mul_f32_e32 v232, v40, v232
	v_cvt_pk_bf16_f32 v232, v232, v161
	v_lshlrev_b32_e32 v233, 16, v233
	v_mul_f32_e32 v233, v41, v233
	v_cvt_pk_bf16_f32 v233, v233, v161
	v_lshlrev_b32_e32 v234, 16, v234
	v_mul_f32_e32 v234, v42, v234
	v_cvt_pk_bf16_f32 v234, v234, v161
	v_lshlrev_b32_e32 v235, 16, v235
	v_mul_f32_e32 v235, v43, v235
	v_cvt_pk_bf16_f32 v235, v235, v161
	v_lshlrev_b32_e32 v236, 16, v236
	v_mul_f32_e32 v236, v44, v236
	v_cvt_pk_bf16_f32 v236, v236, v161
	v_lshlrev_b32_e32 v237, 16, v237
	v_mul_f32_e32 v237, v45, v237
	v_cvt_pk_bf16_f32 v237, v237, v161
	v_lshlrev_b32_e32 v238, 16, v238
	v_mul_f32_e32 v238, v46, v238
	v_cvt_pk_bf16_f32 v238, v238, v161
	v_lshlrev_b32_e32 v239, 16, v239
	v_mul_f32_e32 v239, v47, v239
	v_cvt_pk_bf16_f32 v239, v239, v161
	global_store_short v134, v224, s[20:21] offset:64
	global_store_short v135, v225, s[20:21] offset:64
	global_store_short v136, v226, s[20:21] offset:64
	global_store_short v137, v227, s[20:21] offset:64
	global_store_short v138, v228, s[20:21] offset:64
	global_store_short v139, v229, s[20:21] offset:64
	global_store_short v140, v230, s[20:21] offset:64
	global_store_short v141, v231, s[20:21] offset:64
	global_store_short v142, v232, s[20:21] offset:64
	global_store_short v143, v233, s[20:21] offset:64
	global_store_short v144, v234, s[20:21] offset:64
	global_store_short v145, v235, s[20:21] offset:64
	global_store_short v146, v236, s[20:21] offset:64
	global_store_short v147, v237, s[20:21] offset:64
	global_store_short v148, v238, s[20:21] offset:64
	global_store_short v149, v239, s[20:21] offset:64
	s_waitcnt vmcnt(32)
; __device__ __forceinline__ unsigned cvt_pk_bf16(float lo, float hi) { unsigned r; asm volatile("v_cvt_pk_bf16_f32 %0, %1, %2" : "=v"(r) : "v"(lo), "v"(hi)); return r; }
; __device__ __forceinline__ void mix_phase(const int TID, const int BID, PP p, LAS unsigned char* lds) {
;     ...
;         for (int ct = 0; ct < 4; ++ct) {
;             const int cg_ = g * 256 + ch * 128 + ct * 32 + rr; const float gain = p->sgu_v_gain[cg_];
; #pragma unroll
;             for (int r = 0; r < 16; ++r) {
;                 const int i = it_ * 32 + (r & 3) + 8 * (r >> 2) + 4 * g2; const size_t tok = (size_t)n * 128 + i;
;                 const float mixed = gain * acc[ct][r] + p->sgu_b_s[g * 128 + i];
;                 const float uval = __uint_as_float((unsigned)uv[tok * 4096 + cg_] << 16);
;                 AB[tok * 2048 + cg_] = (bf16_t)(cvt_pk_bf16(uval * mixed, 0.f) & 0xffffu);
;             }
	v_lshlrev_b32_e32 v240, 16, v240
	v_mul_f32_e32 v240, v16, v240
	v_cvt_pk_bf16_f32 v240, v240, v161
	v_lshlrev_b32_e32 v241, 16, v241
	v_mul_f32_e32 v241, v17, v241
	v_cvt_pk_bf16_f32 v241, v241, v161
	v_lshlrev_b32_e32 v242, 16, v242
	v_mul_f32_e32 v242, v18, v242
	v_cvt_pk_bf16_f32 v242, v242, v161
	v_lshlrev_b32_e32 v243, 16, v243
	v_mul_f32_e32 v243, v19, v243
	v_cvt_pk_bf16_f32 v243, v243, v161
	v_lshlrev_b32_e32 v244, 16, v244
	v_mul_f32_e32 v244, v20, v244
	v_cvt_pk_bf16_f32 v244, v244, v161
	v_lshlrev_b32_e32 v245, 16, v245
	v_mul_f32_e32 v245, v21, v245
	v_cvt_pk_bf16_f32 v245, v245, v161
	v_lshlrev_b32_e32 v246, 16, v246
	v_mul_f32_e32 v246, v22, v246
	v_cvt_pk_bf16_f32 v246, v246, v161
	v_lshlrev_b32_e32 v247, 16, v247
	v_mul_f32_e32 v247, v23, v247
	v_cvt_pk_bf16_f32 v247, v247, v161
	v_lshlrev_b32_e32 v248, 16, v248
	v_mul_f32_e32 v248, v24, v248
	v_cvt_pk_bf16_f32 v248, v248, v161
	v_lshlrev_b32_e32 v249, 16, v249
	v_mul_f32_e32 v249, v25, v249
	v_cvt_pk_bf16_f32 v249, v249, v161
	v_lshlrev_b32_e32 v250, 16, v250
	v_mul_f32_e32 v250, v26, v250
	v_cvt_pk_bf16_f32 v250, v250, v161
	v_lshlrev_b32_e32 v251, 16, v251
	v_mul_f32_e32 v251, v27, v251
	v_cvt_pk_bf16_f32 v251, v251, v161
	v_lshlrev_b32_e32 v252, 16, v252
	v_mul_f32_e32 v252, v28, v252
	v_cvt_pk_bf16_f32 v252, v252, v161
	v_lshlrev_b32_e32 v253, 16, v253
	v_mul_f32_e32 v253, v29, v253
	v_cvt_pk_bf16_f32 v253, v253, v161
	v_lshlrev_b32_e32 v198, 16, v198
	v_mul_f32_e32 v198, v30, v198
	v_cvt_pk_bf16_f32 v198, v198, v161
	v_lshlrev_b32_e32 v199, 16, v199
	v_mul_f32_e32 v199, v31, v199
	v_cvt_pk_bf16_f32 v199, v199, v161
	global_store_short v134, v240, s[20:21] offset:128
	global_store_short v135, v241, s[20:21] offset:128
	global_store_short v136, v242, s[20:21] offset:128
	global_store_short v137, v243, s[20:21] offset:128
	global_store_short v138, v244, s[20:21] offset:128
	global_store_short v139, v245, s[20:21] offset:128
	global_store_short v140, v246, s[20:21] offset:128
	global_store_short v141, v247, s[20:21] offset:128
	global_store_short v142, v248, s[20:21] offset:128
	global_store_short v143, v249, s[20:21] offset:128
	global_store_short v144, v250, s[20:21] offset:128
	global_store_short v145, v251, s[20:21] offset:128
	global_store_short v146, v252, s[20:21] offset:128
	global_store_short v147, v253, s[20:21] offset:128
	global_store_short v148, v198, s[20:21] offset:128
	global_store_short v149, v199, s[20:21] offset:128
	s_waitcnt vmcnt(47)
	v_lshlrev_b32_e32 v150, 16, v150
	v_mul_f32_e32 v150, v0, v150
	v_cvt_pk_bf16_f32 v150, v150, v161
	v_lshlrev_b32_e32 v151, 16, v151
	v_mul_f32_e32 v151, v1, v151
	v_cvt_pk_bf16_f32 v151, v151, v161
	v_lshlrev_b32_e32 v152, 16, v152
	v_mul_f32_e32 v152, v2, v152
	v_cvt_pk_bf16_f32 v152, v152, v161
	v_lshlrev_b32_e32 v153, 16, v153
	v_mul_f32_e32 v153, v3, v153
	v_cvt_pk_bf16_f32 v153, v153, v161
	v_lshlrev_b32_e32 v154, 16, v154
	v_mul_f32_e32 v154, v4, v154
	v_cvt_pk_bf16_f32 v154, v154, v161
	v_lshlrev_b32_e32 v155, 16, v155
	v_mul_f32_e32 v155, v5, v155
	v_cvt_pk_bf16_f32 v155, v155, v161
	v_lshlrev_b32_e32 v156, 16, v156
	v_mul_f32_e32 v156, v6, v156
	v_cvt_pk_bf16_f32 v156, v156, v161
	v_lshlrev_b32_e32 v157, 16, v157
	v_mul_f32_e32 v157, v7, v157
	v_cvt_pk_bf16_f32 v157, v157, v161
	v_lshlrev_b32_e32 v158, 16, v158
	v_mul_f32_e32 v158, v8, v158
	v_cvt_pk_bf16_f32 v158, v158, v161
	v_lshlrev_b32_e32 v159, 16, v159
	v_mul_f32_e32 v159, v9, v159
	v_cvt_pk_bf16_f32 v159, v159, v161
	v_lshlrev_b32_e32 v114, 16, v114
	v_mul_f32_e32 v114, v10, v114
	v_cvt_pk_bf16_f32 v114, v114, v161
	v_lshlrev_b32_e32 v115, 16, v115
	v_mul_f32_e32 v115, v11, v115
	v_cvt_pk_bf16_f32 v115, v115, v161
	v_lshlrev_b32_e32 v196, 16, v196
	v_mul_f32_e32 v196, v12, v196
	v_cvt_pk_bf16_f32 v196, v196, v161
	v_lshlrev_b32_e32 v197, 16, v197
	v_mul_f32_e32 v197, v13, v197
	v_cvt_pk_bf16_f32 v197, v197, v161
	v_lshlrev_b32_e32 v200, 16, v200
	v_mul_f32_e32 v200, v14, v200
	v_cvt_pk_bf16_f32 v200, v200, v161
	v_lshlrev_b32_e32 v201, 16, v201
	v_mul_f32_e32 v201, v15, v201
	v_cvt_pk_bf16_f32 v201, v201, v161
	global_store_short v134, v150, s[20:21] offset:192
	global_store_short v135, v151, s[20:21] offset:192
	global_store_short v136, v152, s[20:21] offset:192
	global_store_short v137, v153, s[20:21] offset:192
	global_store_short v138, v154, s[20:21] offset:192
	global_store_short v139, v155, s[20:21] offset:192
	global_store_short v140, v156, s[20:21] offset:192
	global_store_short v141, v157, s[20:21] offset:192
	global_store_short v142, v158, s[20:21] offset:192
	global_store_short v143, v159, s[20:21] offset:192
	global_store_short v144, v114, s[20:21] offset:192
	global_store_short v145, v115, s[20:21] offset:192
	global_store_short v146, v196, s[20:21] offset:192
	global_store_short v147, v197, s[20:21] offset:192
	global_store_short v148, v200, s[20:21] offset:192
	global_store_short v149, v201, s[20:21] offset:192
	s_cbranch_scc1 .LBB0_845
